# prologue row loop split 4 rows (weight-conversion-heavy workgroups 0..127) / 12 rows (128..255) after the W_up conversion rewrite
# speedup vs baseline: 1.0081x; 1.0000x over previous
; DI void st_bf4(bf16_t* p, f32x4 v) { u32x2 w; w.x = pk2(v[0], v[1]); w.y = pk2(v[2], v[3]); *(u32x2*)p = w; }
;     DI bf16_t* hb() const { return (bf16_t*)(ws + WS_HB); }
;     DI float* ssqh() const { return (float*)(ws + WS_SSQH); }
;     DI const float* gin(int i) const { return (const float*)(const __attribute__((address_space(1))) float*)kp->in[i]; }
; DI void phase_prep(Frame& F) {
;     ...
;     for (int row = F.gw; row < M; row += F.ngw) {
;         const f32x4* xr = (const f32x4*)(F.gin(0) + (size_t)row * DM) + F.lane; float s = 0.f;
; #pragma unroll
;         for (int j = 0; j < 4; ++j) { f32x4 v = xr[64 * j]; s += (v[0] * v[0] + v[1] * v[1]) + (v[2] * v[2] + v[3] * v[3]);
;             st_bf4(F.hb() + (size_t)row * DM + 4 * (F.lane + 64 * j), v); }
;         s = wave_sum(s);
;         if (F.lane < 16) F.ssqh()[(size_t)row * 16 + F.lane] = F.lane == 0 ? s : 0.f;
.LBB0_2080:
	v_readlane_b32 s16, v254, 24
	v_readlane_b32 s17, v254, 25
	v_readlane_b32 s44, v254, 22
	v_readlane_b32 s45, v254, 23
	v_readlane_b32 s10, v254, 20
	v_readlane_b32 s11, v254, 21
	v_lshl_add_u64 v[32:33], s[76:77], 0, v[6:7]
	s_mov_b32 s24, 0xcd10000
	s_mov_b32 s25, 0
	v_lshl_add_u64 v[32:33], v[32:33], 0, s[24:25]
	v_lshl_add_u64 v[210:211], s[76:77], 0, v[4:5]
	s_cmp_lt_u32 s2, 128
	s_cbranch_scc0 .Lxhb_light
	global_load_dwordx4 v[36:39], v[8:9], off offset:-3072
	global_load_dwordx4 v[40:43], v[8:9], off offset:-2048
	global_load_dwordx4 v[44:47], v[8:9], off offset:-1024
	global_load_dwordx4 v[48:51], v[8:9], off
	v_lshl_add_u64 v[8:9], v[8:9], 0, s[16:17]
	global_load_dwordx4 v[52:55], v[8:9], off offset:-3072
	global_load_dwordx4 v[56:59], v[8:9], off offset:-2048
	global_load_dwordx4 v[60:63], v[8:9], off offset:-1024
	global_load_dwordx4 v[64:67], v[8:9], off
	v_lshl_add_u64 v[8:9], v[8:9], 0, s[16:17]
	global_load_dwordx4 v[68:71], v[8:9], off offset:-3072
	global_load_dwordx4 v[72:75], v[8:9], off offset:-2048
	global_load_dwordx4 v[76:79], v[8:9], off offset:-1024
	global_load_dwordx4 v[80:83], v[8:9], off
	v_lshl_add_u64 v[8:9], v[8:9], 0, s[16:17]
	global_load_dwordx4 v[84:87], v[8:9], off offset:-3072
	global_load_dwordx4 v[88:91], v[8:9], off offset:-2048
	global_load_dwordx4 v[92:95], v[8:9], off offset:-1024
	global_load_dwordx4 v[96:99], v[8:9], off
	s_waitcnt vmcnt(12)
	v_mul_f32_e32 v0, v37, v37
	v_mul_f32_e32 v3, v39, v39
	v_fmac_f32_e32 v0, v36, v36
	v_fmac_f32_e32 v3, v38, v38
	v_add_f32_e32 v16, v0, v3
	v_mul_f32_e32 v0, v41, v41
	v_mul_f32_e32 v3, v43, v43
	v_fmac_f32_e32 v0, v40, v40
	v_fmac_f32_e32 v3, v42, v42
	v_add_f32_e32 v0, v0, v3
	v_add_f32_e32 v16, v16, v0
	v_mul_f32_e32 v0, v45, v45
	v_mul_f32_e32 v3, v47, v47
	v_fmac_f32_e32 v0, v44, v44
	v_fmac_f32_e32 v3, v46, v46
	v_add_f32_e32 v0, v0, v3
	v_add_f32_e32 v16, v16, v0
	v_mul_f32_e32 v0, v49, v49
	v_mul_f32_e32 v3, v51, v51
	v_fmac_f32_e32 v0, v48, v48
	v_fmac_f32_e32 v3, v50, v50
	v_add_f32_e32 v0, v0, v3
	v_add_f32_e32 v16, v16, v0
	v_cvt_pk_bf16_f32 v36, v36, v37
	v_cvt_pk_bf16_f32 v37, v38, v39
	v_cvt_pk_bf16_f32 v40, v40, v41
	v_cvt_pk_bf16_f32 v41, v42, v43
	v_cvt_pk_bf16_f32 v44, v44, v45
	v_cvt_pk_bf16_f32 v45, v46, v47
	v_cvt_pk_bf16_f32 v48, v48, v49
	v_cvt_pk_bf16_f32 v49, v50, v51
	global_store_dwordx2 v[32:33], v[36:37], off
	global_store_dwordx2 v[32:33], v[40:41], off offset:512
	global_store_dwordx2 v[32:33], v[44:45], off offset:1024
	global_store_dwordx2 v[32:33], v[48:49], off offset:1536
	v_lshl_add_u64 v[32:33], v[32:33], 0, s[44:45]
	s_waitcnt vmcnt(12)
	v_mul_f32_e32 v0, v53, v53
	v_mul_f32_e32 v3, v55, v55
	v_fmac_f32_e32 v0, v52, v52
	v_fmac_f32_e32 v3, v54, v54
	v_add_f32_e32 v17, v0, v3
	v_mul_f32_e32 v0, v57, v57
	v_mul_f32_e32 v3, v59, v59
	v_fmac_f32_e32 v0, v56, v56
	v_fmac_f32_e32 v3, v58, v58
	v_add_f32_e32 v0, v0, v3
	v_add_f32_e32 v17, v17, v0
	v_mul_f32_e32 v0, v61, v61
	v_mul_f32_e32 v3, v63, v63
	v_fmac_f32_e32 v0, v60, v60
	v_fmac_f32_e32 v3, v62, v62
	v_add_f32_e32 v0, v0, v3
	v_add_f32_e32 v17, v17, v0
	v_mul_f32_e32 v0, v65, v65
	v_mul_f32_e32 v3, v67, v67
	v_fmac_f32_e32 v0, v64, v64
	v_fmac_f32_e32 v3, v66, v66
	v_add_f32_e32 v0, v0, v3
	v_add_f32_e32 v17, v17, v0
	v_cvt_pk_bf16_f32 v52, v52, v53
	v_cvt_pk_bf16_f32 v53, v54, v55
	v_cvt_pk_bf16_f32 v56, v56, v57
	v_cvt_pk_bf16_f32 v57, v58, v59
	v_cvt_pk_bf16_f32 v60, v60, v61
	v_cvt_pk_bf16_f32 v61, v62, v63
	v_cvt_pk_bf16_f32 v64, v64, v65
	v_cvt_pk_bf16_f32 v65, v66, v67
	global_store_dwordx2 v[32:33], v[52:53], off
	global_store_dwordx2 v[32:33], v[56:57], off offset:512
	global_store_dwordx2 v[32:33], v[60:61], off offset:1024
	global_store_dwordx2 v[32:33], v[64:65], off offset:1536
	v_lshl_add_u64 v[32:33], v[32:33], 0, s[44:45]
	s_waitcnt vmcnt(12)
	v_mul_f32_e32 v0, v69, v69
	v_mul_f32_e32 v3, v71, v71
	v_fmac_f32_e32 v0, v68, v68
	v_fmac_f32_e32 v3, v70, v70
	v_add_f32_e32 v18, v0, v3
	v_mul_f32_e32 v0, v73, v73
	v_mul_f32_e32 v3, v75, v75
	v_fmac_f32_e32 v0, v72, v72
	v_fmac_f32_e32 v3, v74, v74
	v_add_f32_e32 v0, v0, v3
	v_add_f32_e32 v18, v18, v0
	v_mul_f32_e32 v0, v77, v77
	v_mul_f32_e32 v3, v79, v79
	v_fmac_f32_e32 v0, v76, v76
	v_fmac_f32_e32 v3, v78, v78
	v_add_f32_e32 v0, v0, v3
	v_add_f32_e32 v18, v18, v0
	v_mul_f32_e32 v0, v81, v81
	v_mul_f32_e32 v3, v83, v83
	v_fmac_f32_e32 v0, v80, v80
	v_fmac_f32_e32 v3, v82, v82
	v_add_f32_e32 v0, v0, v3
	v_add_f32_e32 v18, v18, v0
	v_cvt_pk_bf16_f32 v68, v68, v69
	v_cvt_pk_bf16_f32 v69, v70, v71
	v_cvt_pk_bf16_f32 v72, v72, v73
	v_cvt_pk_bf16_f32 v73, v74, v75
	v_cvt_pk_bf16_f32 v76, v76, v77
	v_cvt_pk_bf16_f32 v77, v78, v79
	v_cvt_pk_bf16_f32 v80, v80, v81
	v_cvt_pk_bf16_f32 v81, v82, v83
	global_store_dwordx2 v[32:33], v[68:69], off
	global_store_dwordx2 v[32:33], v[72:73], off offset:512
	global_store_dwordx2 v[32:33], v[76:77], off offset:1024
	global_store_dwordx2 v[32:33], v[80:81], off offset:1536
	v_lshl_add_u64 v[32:33], v[32:33], 0, s[44:45]
	s_waitcnt vmcnt(12)
; DI void st_bf4(bf16_t* p, f32x4 v) { u32x2 w; w.x = pk2(v[0], v[1]); w.y = pk2(v[2], v[3]); *(u32x2*)p = w; }
;     DI bf16_t* hb() const { return (bf16_t*)(ws + WS_HB); }
;     DI float* ssqh() const { return (float*)(ws + WS_SSQH); }
;     DI const float* gin(int i) const { return (const float*)(const __attribute__((address_space(1))) float*)kp->in[i]; }
; DI float wave_sum(float v) {
; #pragma unroll
;     for (int o = 1; o < 64; o <<= 1) v += __shfl_xor(v, o);
;     return v;
; }
; DI void phase_prep(Frame& F) {
;     ...
;     for (int row = F.gw; row < M; row += F.ngw) {
;         const f32x4* xr = (const f32x4*)(F.gin(0) + (size_t)row * DM) + F.lane; float s = 0.f;
; #pragma unroll
;         for (int j = 0; j < 4; ++j) { f32x4 v = xr[64 * j]; s += (v[0] * v[0] + v[1] * v[1]) + (v[2] * v[2] + v[3] * v[3]);
;             st_bf4(F.hb() + (size_t)row * DM + 4 * (F.lane + 64 * j), v); }
;         s = wave_sum(s);
;         if (F.lane < 16) F.ssqh()[(size_t)row * 16 + F.lane] = F.lane == 0 ? s : 0.f;
	v_mul_f32_e32 v0, v85, v85
	v_mul_f32_e32 v3, v87, v87
	v_fmac_f32_e32 v0, v84, v84
	v_fmac_f32_e32 v3, v86, v86
	v_add_f32_e32 v19, v0, v3
	v_mul_f32_e32 v0, v89, v89
	v_mul_f32_e32 v3, v91, v91
	v_fmac_f32_e32 v0, v88, v88
	v_fmac_f32_e32 v3, v90, v90
	v_add_f32_e32 v0, v0, v3
	v_add_f32_e32 v19, v19, v0
	v_mul_f32_e32 v0, v93, v93
	v_mul_f32_e32 v3, v95, v95
	v_fmac_f32_e32 v0, v92, v92
	v_fmac_f32_e32 v3, v94, v94
	v_add_f32_e32 v0, v0, v3
	v_add_f32_e32 v19, v19, v0
	v_mul_f32_e32 v0, v97, v97
	v_mul_f32_e32 v3, v99, v99
	v_fmac_f32_e32 v0, v96, v96
	v_fmac_f32_e32 v3, v98, v98
	v_add_f32_e32 v0, v0, v3
	v_add_f32_e32 v19, v19, v0
	v_cvt_pk_bf16_f32 v84, v84, v85
	v_cvt_pk_bf16_f32 v85, v86, v87
	v_cvt_pk_bf16_f32 v88, v88, v89
	v_cvt_pk_bf16_f32 v89, v90, v91
	v_cvt_pk_bf16_f32 v92, v92, v93
	v_cvt_pk_bf16_f32 v93, v94, v95
	v_cvt_pk_bf16_f32 v96, v96, v97
	v_cvt_pk_bf16_f32 v97, v98, v99
	global_store_dwordx2 v[32:33], v[84:85], off
	global_store_dwordx2 v[32:33], v[88:89], off offset:512
	global_store_dwordx2 v[32:33], v[92:93], off offset:1024
	global_store_dwordx2 v[32:33], v[96:97], off offset:1536
	ds_bpermute_b32 v24, v10, v16
	ds_bpermute_b32 v25, v10, v17
	ds_bpermute_b32 v26, v10, v18
	ds_bpermute_b32 v27, v10, v19
	s_waitcnt lgkmcnt(0)
	v_add_f32_e32 v16, v16, v24
	v_add_f32_e32 v17, v17, v25
	v_add_f32_e32 v18, v18, v26
	v_add_f32_e32 v19, v19, v27
	ds_bpermute_b32 v24, v11, v16
	ds_bpermute_b32 v25, v11, v17
	ds_bpermute_b32 v26, v11, v18
	ds_bpermute_b32 v27, v11, v19
	s_waitcnt lgkmcnt(0)
	v_add_f32_e32 v16, v16, v24
	v_add_f32_e32 v17, v17, v25
	v_add_f32_e32 v18, v18, v26
	v_add_f32_e32 v19, v19, v27
	ds_bpermute_b32 v24, v12, v16
	ds_bpermute_b32 v25, v12, v17
	ds_bpermute_b32 v26, v12, v18
	ds_bpermute_b32 v27, v12, v19
	s_waitcnt lgkmcnt(0)
	v_add_f32_e32 v16, v16, v24
	v_add_f32_e32 v17, v17, v25
	v_add_f32_e32 v18, v18, v26
	v_add_f32_e32 v19, v19, v27
	ds_bpermute_b32 v24, v13, v16
	ds_bpermute_b32 v25, v13, v17
	ds_bpermute_b32 v26, v13, v18
	ds_bpermute_b32 v27, v13, v19
	s_waitcnt lgkmcnt(0)
	v_add_f32_e32 v16, v16, v24
	v_add_f32_e32 v17, v17, v25
	v_add_f32_e32 v18, v18, v26
	v_add_f32_e32 v19, v19, v27
	ds_bpermute_b32 v24, v14, v16
	ds_bpermute_b32 v25, v14, v17
	ds_bpermute_b32 v26, v14, v18
	ds_bpermute_b32 v27, v14, v19
	s_waitcnt lgkmcnt(0)
	v_add_f32_e32 v16, v16, v24
	v_add_f32_e32 v17, v17, v25
	v_add_f32_e32 v18, v18, v26
	v_add_f32_e32 v19, v19, v27
	ds_bpermute_b32 v24, v15, v16
	ds_bpermute_b32 v25, v15, v17
	ds_bpermute_b32 v26, v15, v18
	ds_bpermute_b32 v27, v15, v19
	s_waitcnt lgkmcnt(0)
	v_add_f32_e32 v16, v16, v24
	v_add_f32_e32 v17, v17, v25
	v_add_f32_e32 v18, v18, v26
	v_add_f32_e32 v19, v19, v27
	v_cndmask_b32_e64 v16, 0, v16, s[42:43]
	v_cndmask_b32_e64 v17, 0, v17, s[42:43]
	v_cndmask_b32_e64 v18, 0, v18, s[42:43]
	v_cndmask_b32_e64 v19, 0, v19, s[42:43]
	s_and_saveexec_b64 s[24:25], vcc
	global_store_dword v[210:211], v16, off
	v_lshl_add_u64 v[210:211], v[210:211], 0, s[10:11]
	global_store_dword v[210:211], v17, off
	v_lshl_add_u64 v[210:211], v[210:211], 0, s[10:11]
	global_store_dword v[210:211], v18, off
	v_lshl_add_u64 v[210:211], v[210:211], 0, s[10:11]
	global_store_dword v[210:211], v19, off
	s_or_b64 exec, exec, s[24:25]
	s_branch .LBB0_2082
.Lxhb_light:
	global_load_dwordx4 v[36:39], v[8:9], off offset:-3072
	global_load_dwordx4 v[40:43], v[8:9], off offset:-2048
	global_load_dwordx4 v[44:47], v[8:9], off offset:-1024
	global_load_dwordx4 v[48:51], v[8:9], off
	v_lshl_add_u64 v[8:9], v[8:9], 0, s[16:17]
	global_load_dwordx4 v[52:55], v[8:9], off offset:-3072
	global_load_dwordx4 v[56:59], v[8:9], off offset:-2048
	global_load_dwordx4 v[60:63], v[8:9], off offset:-1024
	global_load_dwordx4 v[64:67], v[8:9], off
	v_lshl_add_u64 v[8:9], v[8:9], 0, s[16:17]
	global_load_dwordx4 v[68:71], v[8:9], off offset:-3072
	global_load_dwordx4 v[72:75], v[8:9], off offset:-2048
	global_load_dwordx4 v[76:79], v[8:9], off offset:-1024
	global_load_dwordx4 v[80:83], v[8:9], off
	v_lshl_add_u64 v[8:9], v[8:9], 0, s[16:17]
	global_load_dwordx4 v[84:87], v[8:9], off offset:-3072
	global_load_dwordx4 v[88:91], v[8:9], off offset:-2048
	global_load_dwordx4 v[92:95], v[8:9], off offset:-1024
	global_load_dwordx4 v[96:99], v[8:9], off
	v_lshl_add_u64 v[8:9], v[8:9], 0, s[16:17]
	global_load_dwordx4 v[100:103], v[8:9], off offset:-3072
	global_load_dwordx4 v[104:107], v[8:9], off offset:-2048
	global_load_dwordx4 v[108:111], v[8:9], off offset:-1024
	global_load_dwordx4 v[112:115], v[8:9], off
	v_lshl_add_u64 v[8:9], v[8:9], 0, s[16:17]
	global_load_dwordx4 v[116:119], v[8:9], off offset:-3072
	global_load_dwordx4 v[120:123], v[8:9], off offset:-2048
	global_load_dwordx4 v[124:127], v[8:9], off offset:-1024
	global_load_dwordx4 v[128:131], v[8:9], off
	v_lshl_add_u64 v[8:9], v[8:9], 0, s[16:17]
	global_load_dwordx4 v[132:135], v[8:9], off offset:-3072
	global_load_dwordx4 v[188:191], v[8:9], off offset:-2048
	global_load_dwordx4 v[192:195], v[8:9], off offset:-1024
	global_load_dwordx4 v[196:199], v[8:9], off
	v_lshl_add_u64 v[8:9], v[8:9], 0, s[16:17]
	global_load_dwordx4 v[200:203], v[8:9], off offset:-3072
	global_load_dwordx4 v[204:207], v[8:9], off offset:-2048
	global_load_dwordx4 v[236:239], v[8:9], off offset:-1024
	global_load_dwordx4 v[240:243], v[8:9], off
	s_waitcnt vmcnt(28)
; DI void st_bf4(bf16_t* p, f32x4 v) { u32x2 w; w.x = pk2(v[0], v[1]); w.y = pk2(v[2], v[3]); *(u32x2*)p = w; }
;     DI bf16_t* hb() const { return (bf16_t*)(ws + WS_HB); }
;     DI const float* gin(int i) const { return (const float*)(const __attribute__((address_space(1))) float*)kp->in[i]; }
; DI void phase_prep(Frame& F) {
;     ...
;     for (int row = F.gw; row < M; row += F.ngw) {
;         const f32x4* xr = (const f32x4*)(F.gin(0) + (size_t)row * DM) + F.lane; float s = 0.f;
; #pragma unroll
;         for (int j = 0; j < 4; ++j) { f32x4 v = xr[64 * j]; s += (v[0] * v[0] + v[1] * v[1]) + (v[2] * v[2] + v[3] * v[3]);
;             st_bf4(F.hb() + (size_t)row * DM + 4 * (F.lane + 64 * j), v); }
	v_mul_f32_e32 v0, v37, v37
	v_mul_f32_e32 v3, v39, v39
	v_fmac_f32_e32 v0, v36, v36
	v_fmac_f32_e32 v3, v38, v38
	v_add_f32_e32 v16, v0, v3
	v_mul_f32_e32 v0, v41, v41
	v_mul_f32_e32 v3, v43, v43
	v_fmac_f32_e32 v0, v40, v40
	v_fmac_f32_e32 v3, v42, v42
	v_add_f32_e32 v0, v0, v3
	v_add_f32_e32 v16, v16, v0
	v_mul_f32_e32 v0, v45, v45
	v_mul_f32_e32 v3, v47, v47
	v_fmac_f32_e32 v0, v44, v44
	v_fmac_f32_e32 v3, v46, v46
	v_add_f32_e32 v0, v0, v3
	v_add_f32_e32 v16, v16, v0
	v_mul_f32_e32 v0, v49, v49
	v_mul_f32_e32 v3, v51, v51
	v_fmac_f32_e32 v0, v48, v48
	v_fmac_f32_e32 v3, v50, v50
	v_add_f32_e32 v0, v0, v3
	v_add_f32_e32 v16, v16, v0
	v_cvt_pk_bf16_f32 v36, v36, v37
	v_cvt_pk_bf16_f32 v37, v38, v39
	v_cvt_pk_bf16_f32 v40, v40, v41
	v_cvt_pk_bf16_f32 v41, v42, v43
	v_cvt_pk_bf16_f32 v44, v44, v45
	v_cvt_pk_bf16_f32 v45, v46, v47
	v_cvt_pk_bf16_f32 v48, v48, v49
	v_cvt_pk_bf16_f32 v49, v50, v51
	global_store_dwordx2 v[32:33], v[36:37], off
	global_store_dwordx2 v[32:33], v[40:41], off offset:512
	global_store_dwordx2 v[32:33], v[44:45], off offset:1024
	global_store_dwordx2 v[32:33], v[48:49], off offset:1536
	v_lshl_add_u64 v[32:33], v[32:33], 0, s[44:45]
	s_waitcnt vmcnt(28)
	v_mul_f32_e32 v0, v53, v53
	v_mul_f32_e32 v3, v55, v55
	v_fmac_f32_e32 v0, v52, v52
	v_fmac_f32_e32 v3, v54, v54
	v_add_f32_e32 v17, v0, v3
	v_mul_f32_e32 v0, v57, v57
	v_mul_f32_e32 v3, v59, v59
	v_fmac_f32_e32 v0, v56, v56
	v_fmac_f32_e32 v3, v58, v58
	v_add_f32_e32 v0, v0, v3
	v_add_f32_e32 v17, v17, v0
	v_mul_f32_e32 v0, v61, v61
	v_mul_f32_e32 v3, v63, v63
	v_fmac_f32_e32 v0, v60, v60
	v_fmac_f32_e32 v3, v62, v62
	v_add_f32_e32 v0, v0, v3
	v_add_f32_e32 v17, v17, v0
	v_mul_f32_e32 v0, v65, v65
	v_mul_f32_e32 v3, v67, v67
	v_fmac_f32_e32 v0, v64, v64
	v_fmac_f32_e32 v3, v66, v66
	v_add_f32_e32 v0, v0, v3
	v_add_f32_e32 v17, v17, v0
	v_cvt_pk_bf16_f32 v52, v52, v53
	v_cvt_pk_bf16_f32 v53, v54, v55
	v_cvt_pk_bf16_f32 v56, v56, v57
	v_cvt_pk_bf16_f32 v57, v58, v59
	v_cvt_pk_bf16_f32 v60, v60, v61
	v_cvt_pk_bf16_f32 v61, v62, v63
	v_cvt_pk_bf16_f32 v64, v64, v65
	v_cvt_pk_bf16_f32 v65, v66, v67
	global_store_dwordx2 v[32:33], v[52:53], off
	global_store_dwordx2 v[32:33], v[56:57], off offset:512
	global_store_dwordx2 v[32:33], v[60:61], off offset:1024
	global_store_dwordx2 v[32:33], v[64:65], off offset:1536
	v_lshl_add_u64 v[32:33], v[32:33], 0, s[44:45]
	s_waitcnt vmcnt(28)
	v_mul_f32_e32 v0, v69, v69
	v_mul_f32_e32 v3, v71, v71
	v_fmac_f32_e32 v0, v68, v68
	v_fmac_f32_e32 v3, v70, v70
	v_add_f32_e32 v18, v0, v3
	v_mul_f32_e32 v0, v73, v73
	v_mul_f32_e32 v3, v75, v75
	v_fmac_f32_e32 v0, v72, v72
	v_fmac_f32_e32 v3, v74, v74
	v_add_f32_e32 v0, v0, v3
	v_add_f32_e32 v18, v18, v0
	v_mul_f32_e32 v0, v77, v77
	v_mul_f32_e32 v3, v79, v79
	v_fmac_f32_e32 v0, v76, v76
	v_fmac_f32_e32 v3, v78, v78
	v_add_f32_e32 v0, v0, v3
	v_add_f32_e32 v18, v18, v0
	v_mul_f32_e32 v0, v81, v81
	v_mul_f32_e32 v3, v83, v83
	v_fmac_f32_e32 v0, v80, v80
	v_fmac_f32_e32 v3, v82, v82
	v_add_f32_e32 v0, v0, v3
	v_add_f32_e32 v18, v18, v0
	v_cvt_pk_bf16_f32 v68, v68, v69
	v_cvt_pk_bf16_f32 v69, v70, v71
	v_cvt_pk_bf16_f32 v72, v72, v73
	v_cvt_pk_bf16_f32 v73, v74, v75
	v_cvt_pk_bf16_f32 v76, v76, v77
	v_cvt_pk_bf16_f32 v77, v78, v79
	v_cvt_pk_bf16_f32 v80, v80, v81
	v_cvt_pk_bf16_f32 v81, v82, v83
	global_store_dwordx2 v[32:33], v[68:69], off
	global_store_dwordx2 v[32:33], v[72:73], off offset:512
	global_store_dwordx2 v[32:33], v[76:77], off offset:1024
	global_store_dwordx2 v[32:33], v[80:81], off offset:1536
	v_lshl_add_u64 v[32:33], v[32:33], 0, s[44:45]
	s_waitcnt vmcnt(28)
	v_mul_f32_e32 v0, v85, v85
	v_mul_f32_e32 v3, v87, v87
	v_fmac_f32_e32 v0, v84, v84
	v_fmac_f32_e32 v3, v86, v86
	v_add_f32_e32 v19, v0, v3
	v_mul_f32_e32 v0, v89, v89
	v_mul_f32_e32 v3, v91, v91
	v_fmac_f32_e32 v0, v88, v88
	v_fmac_f32_e32 v3, v90, v90
	v_add_f32_e32 v0, v0, v3
	v_add_f32_e32 v19, v19, v0
	v_mul_f32_e32 v0, v93, v93
	v_mul_f32_e32 v3, v95, v95
	v_fmac_f32_e32 v0, v92, v92
	v_fmac_f32_e32 v3, v94, v94
	v_add_f32_e32 v0, v0, v3
	v_add_f32_e32 v19, v19, v0
	v_mul_f32_e32 v0, v97, v97
	v_mul_f32_e32 v3, v99, v99
	v_fmac_f32_e32 v0, v96, v96
	v_fmac_f32_e32 v3, v98, v98
	v_add_f32_e32 v0, v0, v3
	v_add_f32_e32 v19, v19, v0
	v_cvt_pk_bf16_f32 v84, v84, v85
	v_cvt_pk_bf16_f32 v85, v86, v87
	v_cvt_pk_bf16_f32 v88, v88, v89
	v_cvt_pk_bf16_f32 v89, v90, v91
	v_cvt_pk_bf16_f32 v92, v92, v93
	v_cvt_pk_bf16_f32 v93, v94, v95
	v_cvt_pk_bf16_f32 v96, v96, v97
	v_cvt_pk_bf16_f32 v97, v98, v99
	global_store_dwordx2 v[32:33], v[84:85], off
	global_store_dwordx2 v[32:33], v[88:89], off offset:512
	global_store_dwordx2 v[32:33], v[92:93], off offset:1024
	global_store_dwordx2 v[32:33], v[96:97], off offset:1536
	v_lshl_add_u64 v[32:33], v[32:33], 0, s[44:45]
	s_waitcnt vmcnt(28)
	v_mul_f32_e32 v0, v101, v101
	v_mul_f32_e32 v3, v103, v103
	v_fmac_f32_e32 v0, v100, v100
	v_fmac_f32_e32 v3, v102, v102
	v_add_f32_e32 v20, v0, v3
	v_mul_f32_e32 v0, v105, v105
	v_mul_f32_e32 v3, v107, v107
	v_fmac_f32_e32 v0, v104, v104
	v_fmac_f32_e32 v3, v106, v106
	v_add_f32_e32 v0, v0, v3
	v_add_f32_e32 v20, v20, v0
	v_mul_f32_e32 v0, v109, v109
	v_mul_f32_e32 v3, v111, v111
	v_fmac_f32_e32 v0, v108, v108
	v_fmac_f32_e32 v3, v110, v110
	v_add_f32_e32 v0, v0, v3
	v_add_f32_e32 v20, v20, v0
	v_mul_f32_e32 v0, v113, v113
	v_mul_f32_e32 v3, v115, v115
	v_fmac_f32_e32 v0, v112, v112
	v_fmac_f32_e32 v3, v114, v114
	v_add_f32_e32 v0, v0, v3
	v_add_f32_e32 v20, v20, v0
	v_cvt_pk_bf16_f32 v100, v100, v101
	v_cvt_pk_bf16_f32 v101, v102, v103
	v_cvt_pk_bf16_f32 v104, v104, v105
	v_cvt_pk_bf16_f32 v105, v106, v107
	v_cvt_pk_bf16_f32 v108, v108, v109
	v_cvt_pk_bf16_f32 v109, v110, v111
	v_cvt_pk_bf16_f32 v112, v112, v113
	v_cvt_pk_bf16_f32 v113, v114, v115
	global_store_dwordx2 v[32:33], v[100:101], off
	global_store_dwordx2 v[32:33], v[104:105], off offset:512
	global_store_dwordx2 v[32:33], v[108:109], off offset:1024
	global_store_dwordx2 v[32:33], v[112:113], off offset:1536
	v_lshl_add_u64 v[32:33], v[32:33], 0, s[44:45]
	s_waitcnt vmcnt(28)
; DI void st_bf4(bf16_t* p, f32x4 v) { u32x2 w; w.x = pk2(v[0], v[1]); w.y = pk2(v[2], v[3]); *(u32x2*)p = w; }
;     DI bf16_t* hb() const { return (bf16_t*)(ws + WS_HB); }
;     DI float* ssqh() const { return (float*)(ws + WS_SSQH); }
; DI float wave_sum(float v) {
; #pragma unroll
;     for (int o = 1; o < 64; o <<= 1) v += __shfl_xor(v, o);
;     return v;
; DI void phase_prep(Frame& F) {
;     ...
;         for (int j = 0; j < 4; ++j) { f32x4 v = xr[64 * j]; s += (v[0] * v[0] + v[1] * v[1]) + (v[2] * v[2] + v[3] * v[3]);
;             st_bf4(F.hb() + (size_t)row * DM + 4 * (F.lane + 64 * j), v); }
;         s = wave_sum(s);
;         if (F.lane < 16) F.ssqh()[(size_t)row * 16 + F.lane] = F.lane == 0 ? s : 0.f;
	v_mul_f32_e32 v0, v117, v117
	v_mul_f32_e32 v3, v119, v119
	v_fmac_f32_e32 v0, v116, v116
	v_fmac_f32_e32 v3, v118, v118
	v_add_f32_e32 v21, v0, v3
	v_mul_f32_e32 v0, v121, v121
	v_mul_f32_e32 v3, v123, v123
	v_fmac_f32_e32 v0, v120, v120
	v_fmac_f32_e32 v3, v122, v122
	v_add_f32_e32 v0, v0, v3
	v_add_f32_e32 v21, v21, v0
	v_mul_f32_e32 v0, v125, v125
	v_mul_f32_e32 v3, v127, v127
	v_fmac_f32_e32 v0, v124, v124
	v_fmac_f32_e32 v3, v126, v126
	v_add_f32_e32 v0, v0, v3
	v_add_f32_e32 v21, v21, v0
	v_mul_f32_e32 v0, v129, v129
	v_mul_f32_e32 v3, v131, v131
	v_fmac_f32_e32 v0, v128, v128
	v_fmac_f32_e32 v3, v130, v130
	v_add_f32_e32 v0, v0, v3
	v_add_f32_e32 v21, v21, v0
	v_cvt_pk_bf16_f32 v116, v116, v117
	v_cvt_pk_bf16_f32 v117, v118, v119
	v_cvt_pk_bf16_f32 v120, v120, v121
	v_cvt_pk_bf16_f32 v121, v122, v123
	v_cvt_pk_bf16_f32 v124, v124, v125
	v_cvt_pk_bf16_f32 v125, v126, v127
	v_cvt_pk_bf16_f32 v128, v128, v129
	v_cvt_pk_bf16_f32 v129, v130, v131
	global_store_dwordx2 v[32:33], v[116:117], off
	global_store_dwordx2 v[32:33], v[120:121], off offset:512
	global_store_dwordx2 v[32:33], v[124:125], off offset:1024
	global_store_dwordx2 v[32:33], v[128:129], off offset:1536
	v_lshl_add_u64 v[32:33], v[32:33], 0, s[44:45]
	s_waitcnt vmcnt(28)
	v_mul_f32_e32 v0, v133, v133
	v_mul_f32_e32 v3, v135, v135
	v_fmac_f32_e32 v0, v132, v132
	v_fmac_f32_e32 v3, v134, v134
	v_add_f32_e32 v22, v0, v3
	v_mul_f32_e32 v0, v189, v189
	v_mul_f32_e32 v3, v191, v191
	v_fmac_f32_e32 v0, v188, v188
	v_fmac_f32_e32 v3, v190, v190
	v_add_f32_e32 v0, v0, v3
	v_add_f32_e32 v22, v22, v0
	v_mul_f32_e32 v0, v193, v193
	v_mul_f32_e32 v3, v195, v195
	v_fmac_f32_e32 v0, v192, v192
	v_fmac_f32_e32 v3, v194, v194
	v_add_f32_e32 v0, v0, v3
	v_add_f32_e32 v22, v22, v0
	v_mul_f32_e32 v0, v197, v197
	v_mul_f32_e32 v3, v199, v199
	v_fmac_f32_e32 v0, v196, v196
	v_fmac_f32_e32 v3, v198, v198
	v_add_f32_e32 v0, v0, v3
	v_add_f32_e32 v22, v22, v0
	v_cvt_pk_bf16_f32 v132, v132, v133
	v_cvt_pk_bf16_f32 v133, v134, v135
	v_cvt_pk_bf16_f32 v188, v188, v189
	v_cvt_pk_bf16_f32 v189, v190, v191
	v_cvt_pk_bf16_f32 v192, v192, v193
	v_cvt_pk_bf16_f32 v193, v194, v195
	v_cvt_pk_bf16_f32 v196, v196, v197
	v_cvt_pk_bf16_f32 v197, v198, v199
	global_store_dwordx2 v[32:33], v[132:133], off
	global_store_dwordx2 v[32:33], v[188:189], off offset:512
	global_store_dwordx2 v[32:33], v[192:193], off offset:1024
	global_store_dwordx2 v[32:33], v[196:197], off offset:1536
	v_lshl_add_u64 v[32:33], v[32:33], 0, s[44:45]
	s_waitcnt vmcnt(28)
	v_mul_f32_e32 v0, v201, v201
	v_mul_f32_e32 v3, v203, v203
	v_fmac_f32_e32 v0, v200, v200
	v_fmac_f32_e32 v3, v202, v202
	v_add_f32_e32 v23, v0, v3
	v_mul_f32_e32 v0, v205, v205
	v_mul_f32_e32 v3, v207, v207
	v_fmac_f32_e32 v0, v204, v204
	v_fmac_f32_e32 v3, v206, v206
	v_add_f32_e32 v0, v0, v3
	v_add_f32_e32 v23, v23, v0
	v_mul_f32_e32 v0, v237, v237
	v_mul_f32_e32 v3, v239, v239
	v_fmac_f32_e32 v0, v236, v236
	v_fmac_f32_e32 v3, v238, v238
	v_add_f32_e32 v0, v0, v3
	v_add_f32_e32 v23, v23, v0
	v_mul_f32_e32 v0, v241, v241
	v_mul_f32_e32 v3, v243, v243
	v_fmac_f32_e32 v0, v240, v240
	v_fmac_f32_e32 v3, v242, v242
	v_add_f32_e32 v0, v0, v3
	v_add_f32_e32 v23, v23, v0
	v_cvt_pk_bf16_f32 v200, v200, v201
	v_cvt_pk_bf16_f32 v201, v202, v203
	v_cvt_pk_bf16_f32 v204, v204, v205
	v_cvt_pk_bf16_f32 v205, v206, v207
	v_cvt_pk_bf16_f32 v236, v236, v237
	v_cvt_pk_bf16_f32 v237, v238, v239
	v_cvt_pk_bf16_f32 v240, v240, v241
	v_cvt_pk_bf16_f32 v241, v242, v243
	global_store_dwordx2 v[32:33], v[200:201], off
	global_store_dwordx2 v[32:33], v[204:205], off offset:512
	global_store_dwordx2 v[32:33], v[236:237], off offset:1024
	global_store_dwordx2 v[32:33], v[240:241], off offset:1536
	ds_bpermute_b32 v24, v10, v16
	ds_bpermute_b32 v25, v10, v17
	ds_bpermute_b32 v26, v10, v18
	ds_bpermute_b32 v27, v10, v19
	ds_bpermute_b32 v28, v10, v20
	ds_bpermute_b32 v29, v10, v21
	ds_bpermute_b32 v30, v10, v22
	ds_bpermute_b32 v31, v10, v23
	s_waitcnt lgkmcnt(0)
	v_add_f32_e32 v16, v16, v24
	v_add_f32_e32 v17, v17, v25
	v_add_f32_e32 v18, v18, v26
	v_add_f32_e32 v19, v19, v27
	v_add_f32_e32 v20, v20, v28
	v_add_f32_e32 v21, v21, v29
	v_add_f32_e32 v22, v22, v30
	v_add_f32_e32 v23, v23, v31
	ds_bpermute_b32 v24, v11, v16
	ds_bpermute_b32 v25, v11, v17
	ds_bpermute_b32 v26, v11, v18
	ds_bpermute_b32 v27, v11, v19
	ds_bpermute_b32 v28, v11, v20
	ds_bpermute_b32 v29, v11, v21
	ds_bpermute_b32 v30, v11, v22
	ds_bpermute_b32 v31, v11, v23
	s_waitcnt lgkmcnt(0)
	v_add_f32_e32 v16, v16, v24
	v_add_f32_e32 v17, v17, v25
	v_add_f32_e32 v18, v18, v26
	v_add_f32_e32 v19, v19, v27
	v_add_f32_e32 v20, v20, v28
	v_add_f32_e32 v21, v21, v29
	v_add_f32_e32 v22, v22, v30
	v_add_f32_e32 v23, v23, v31
	ds_bpermute_b32 v24, v12, v16
	ds_bpermute_b32 v25, v12, v17
	ds_bpermute_b32 v26, v12, v18
	ds_bpermute_b32 v27, v12, v19
	ds_bpermute_b32 v28, v12, v20
	ds_bpermute_b32 v29, v12, v21
	ds_bpermute_b32 v30, v12, v22
	ds_bpermute_b32 v31, v12, v23
	s_waitcnt lgkmcnt(0)
	v_add_f32_e32 v16, v16, v24
	v_add_f32_e32 v17, v17, v25
	v_add_f32_e32 v18, v18, v26
	v_add_f32_e32 v19, v19, v27
	v_add_f32_e32 v20, v20, v28
	v_add_f32_e32 v21, v21, v29
	v_add_f32_e32 v22, v22, v30
	v_add_f32_e32 v23, v23, v31
	ds_bpermute_b32 v24, v13, v16
	ds_bpermute_b32 v25, v13, v17
	ds_bpermute_b32 v26, v13, v18
	ds_bpermute_b32 v27, v13, v19
	ds_bpermute_b32 v28, v13, v20
	ds_bpermute_b32 v29, v13, v21
	ds_bpermute_b32 v30, v13, v22
	ds_bpermute_b32 v31, v13, v23
	s_waitcnt lgkmcnt(0)
; DI void st_bf4(bf16_t* p, f32x4 v) { u32x2 w; w.x = pk2(v[0], v[1]); w.y = pk2(v[2], v[3]); *(u32x2*)p = w; }
;     DI bf16_t* hb() const { return (bf16_t*)(ws + WS_HB); }
;     DI float* ssqh() const { return (float*)(ws + WS_SSQH); }
;     DI const float* gin(int i) const { return (const float*)(const __attribute__((address_space(1))) float*)kp->in[i]; }
; DI void phase_prep(Frame& F) {
;     ...
;     for (int row = F.gw; row < M; row += F.ngw) {
;         const f32x4* xr = (const f32x4*)(F.gin(0) + (size_t)row * DM) + F.lane; float s = 0.f;
; #pragma unroll
;         for (int j = 0; j < 4; ++j) { f32x4 v = xr[64 * j]; s += (v[0] * v[0] + v[1] * v[1]) + (v[2] * v[2] + v[3] * v[3]);
;             st_bf4(F.hb() + (size_t)row * DM + 4 * (F.lane + 64 * j), v); }
;         s = wave_sum(s);
;         if (F.lane < 16) F.ssqh()[(size_t)row * 16 + F.lane] = F.lane == 0 ? s : 0.f;
	v_add_f32_e32 v16, v16, v24
	v_add_f32_e32 v17, v17, v25
	v_add_f32_e32 v18, v18, v26
	v_add_f32_e32 v19, v19, v27
	v_add_f32_e32 v20, v20, v28
	v_add_f32_e32 v21, v21, v29
	v_add_f32_e32 v22, v22, v30
	v_add_f32_e32 v23, v23, v31
	ds_bpermute_b32 v24, v14, v16
	ds_bpermute_b32 v25, v14, v17
	ds_bpermute_b32 v26, v14, v18
	ds_bpermute_b32 v27, v14, v19
	ds_bpermute_b32 v28, v14, v20
	ds_bpermute_b32 v29, v14, v21
	ds_bpermute_b32 v30, v14, v22
	ds_bpermute_b32 v31, v14, v23
	s_waitcnt lgkmcnt(0)
	v_add_f32_e32 v16, v16, v24
	v_add_f32_e32 v17, v17, v25
	v_add_f32_e32 v18, v18, v26
	v_add_f32_e32 v19, v19, v27
	v_add_f32_e32 v20, v20, v28
	v_add_f32_e32 v21, v21, v29
	v_add_f32_e32 v22, v22, v30
	v_add_f32_e32 v23, v23, v31
	ds_bpermute_b32 v24, v15, v16
	ds_bpermute_b32 v25, v15, v17
	ds_bpermute_b32 v26, v15, v18
	ds_bpermute_b32 v27, v15, v19
	ds_bpermute_b32 v28, v15, v20
	ds_bpermute_b32 v29, v15, v21
	ds_bpermute_b32 v30, v15, v22
	ds_bpermute_b32 v31, v15, v23
	s_waitcnt lgkmcnt(0)
	v_add_f32_e32 v16, v16, v24
	v_add_f32_e32 v17, v17, v25
	v_add_f32_e32 v18, v18, v26
	v_add_f32_e32 v19, v19, v27
	v_add_f32_e32 v20, v20, v28
	v_add_f32_e32 v21, v21, v29
	v_add_f32_e32 v22, v22, v30
	v_add_f32_e32 v23, v23, v31
	v_cndmask_b32_e64 v16, 0, v16, s[42:43]
	v_cndmask_b32_e64 v17, 0, v17, s[42:43]
	v_cndmask_b32_e64 v18, 0, v18, s[42:43]
	v_cndmask_b32_e64 v19, 0, v19, s[42:43]
	v_cndmask_b32_e64 v20, 0, v20, s[42:43]
	v_cndmask_b32_e64 v21, 0, v21, s[42:43]
	v_cndmask_b32_e64 v22, 0, v22, s[42:43]
	v_cndmask_b32_e64 v23, 0, v23, s[42:43]
	s_and_saveexec_b64 s[24:25], vcc
	global_store_dword v[210:211], v16, off
	v_lshl_add_u64 v[210:211], v[210:211], 0, s[10:11]
	global_store_dword v[210:211], v17, off
	v_lshl_add_u64 v[210:211], v[210:211], 0, s[10:11]
	global_store_dword v[210:211], v18, off
	v_lshl_add_u64 v[210:211], v[210:211], 0, s[10:11]
	global_store_dword v[210:211], v19, off
	v_lshl_add_u64 v[210:211], v[210:211], 0, s[10:11]
	global_store_dword v[210:211], v20, off
	v_lshl_add_u64 v[210:211], v[210:211], 0, s[10:11]
	global_store_dword v[210:211], v21, off
	v_lshl_add_u64 v[210:211], v[210:211], 0, s[10:11]
	global_store_dword v[210:211], v22, off
	v_lshl_add_u64 v[210:211], v[210:211], 0, s[10:11]
	global_store_dword v[210:211], v23, off
	s_or_b64 exec, exec, s[24:25]
	s_waitcnt vmcnt(0)
	s_mov_b32 s24, 0xfe400000
	s_mov_b32 s25, 0xffffffff
	v_lshl_add_u64 v[8:9], v[8:9], 0, s[24:25]
	s_mov_b32 s24, 0xff200000
	s_mov_b32 s25, 0xffffffff
	v_lshl_add_u64 v[32:33], v[32:33], 0, s[24:25]
	s_mov_b32 s24, 0xfff90000
	s_mov_b32 s25, 0xffffffff
	v_lshl_add_u64 v[210:211], v[210:211], 0, s[24:25]
	global_load_dwordx4 v[36:39], v[8:9], off offset:-3072
	global_load_dwordx4 v[40:43], v[8:9], off offset:-2048
	global_load_dwordx4 v[44:47], v[8:9], off offset:-1024
	global_load_dwordx4 v[48:51], v[8:9], off
	v_lshl_add_u64 v[8:9], v[8:9], 0, s[16:17]
	global_load_dwordx4 v[52:55], v[8:9], off offset:-3072
	global_load_dwordx4 v[56:59], v[8:9], off offset:-2048
	global_load_dwordx4 v[60:63], v[8:9], off offset:-1024
	global_load_dwordx4 v[64:67], v[8:9], off
	v_lshl_add_u64 v[8:9], v[8:9], 0, s[16:17]
	global_load_dwordx4 v[68:71], v[8:9], off offset:-3072
	global_load_dwordx4 v[72:75], v[8:9], off offset:-2048
	global_load_dwordx4 v[76:79], v[8:9], off offset:-1024
	global_load_dwordx4 v[80:83], v[8:9], off
	v_lshl_add_u64 v[8:9], v[8:9], 0, s[16:17]
	global_load_dwordx4 v[84:87], v[8:9], off offset:-3072
	global_load_dwordx4 v[88:91], v[8:9], off offset:-2048
	global_load_dwordx4 v[92:95], v[8:9], off offset:-1024
	global_load_dwordx4 v[96:99], v[8:9], off
	s_waitcnt vmcnt(12)
	v_mul_f32_e32 v0, v37, v37
	v_mul_f32_e32 v3, v39, v39
	v_fmac_f32_e32 v0, v36, v36
	v_fmac_f32_e32 v3, v38, v38
	v_add_f32_e32 v16, v0, v3
	v_mul_f32_e32 v0, v41, v41
	v_mul_f32_e32 v3, v43, v43
	v_fmac_f32_e32 v0, v40, v40
	v_fmac_f32_e32 v3, v42, v42
	v_add_f32_e32 v0, v0, v3
	v_add_f32_e32 v16, v16, v0
	v_mul_f32_e32 v0, v45, v45
	v_mul_f32_e32 v3, v47, v47
	v_fmac_f32_e32 v0, v44, v44
	v_fmac_f32_e32 v3, v46, v46
	v_add_f32_e32 v0, v0, v3
	v_add_f32_e32 v16, v16, v0
	v_mul_f32_e32 v0, v49, v49
	v_mul_f32_e32 v3, v51, v51
	v_fmac_f32_e32 v0, v48, v48
	v_fmac_f32_e32 v3, v50, v50
	v_add_f32_e32 v0, v0, v3
	v_add_f32_e32 v16, v16, v0
	v_cvt_pk_bf16_f32 v36, v36, v37
	v_cvt_pk_bf16_f32 v37, v38, v39
	v_cvt_pk_bf16_f32 v40, v40, v41
	v_cvt_pk_bf16_f32 v41, v42, v43
	v_cvt_pk_bf16_f32 v44, v44, v45
	v_cvt_pk_bf16_f32 v45, v46, v47
	v_cvt_pk_bf16_f32 v48, v48, v49
	v_cvt_pk_bf16_f32 v49, v50, v51
	global_store_dwordx2 v[32:33], v[36:37], off
	global_store_dwordx2 v[32:33], v[40:41], off offset:512
	global_store_dwordx2 v[32:33], v[44:45], off offset:1024
	global_store_dwordx2 v[32:33], v[48:49], off offset:1536
	v_lshl_add_u64 v[32:33], v[32:33], 0, s[44:45]
	s_waitcnt vmcnt(12)
; DI void st_bf4(bf16_t* p, f32x4 v) { u32x2 w; w.x = pk2(v[0], v[1]); w.y = pk2(v[2], v[3]); *(u32x2*)p = w; }
;     DI bf16_t* hb() const { return (bf16_t*)(ws + WS_HB); }
;     DI float* ssqh() const { return (float*)(ws + WS_SSQH); }
;     DI const float* gin(int i) const { return (const float*)(const __attribute__((address_space(1))) float*)kp->in[i]; }
; DI void phase_prep(Frame& F) {
;     ...
;     for (int row = F.gw; row < M; row += F.ngw) {
;         const f32x4* xr = (const f32x4*)(F.gin(0) + (size_t)row * DM) + F.lane; float s = 0.f;
; #pragma unroll
;         for (int j = 0; j < 4; ++j) { f32x4 v = xr[64 * j]; s += (v[0] * v[0] + v[1] * v[1]) + (v[2] * v[2] + v[3] * v[3]);
;             st_bf4(F.hb() + (size_t)row * DM + 4 * (F.lane + 64 * j), v); }
;         s = wave_sum(s);
;         if (F.lane < 16) F.ssqh()[(size_t)row * 16 + F.lane] = F.lane == 0 ? s : 0.f;
	v_mul_f32_e32 v0, v53, v53
	v_mul_f32_e32 v3, v55, v55
	v_fmac_f32_e32 v0, v52, v52
	v_fmac_f32_e32 v3, v54, v54
	v_add_f32_e32 v17, v0, v3
	v_mul_f32_e32 v0, v57, v57
	v_mul_f32_e32 v3, v59, v59
	v_fmac_f32_e32 v0, v56, v56
	v_fmac_f32_e32 v3, v58, v58
	v_add_f32_e32 v0, v0, v3
	v_add_f32_e32 v17, v17, v0
	v_mul_f32_e32 v0, v61, v61
	v_mul_f32_e32 v3, v63, v63
	v_fmac_f32_e32 v0, v60, v60
	v_fmac_f32_e32 v3, v62, v62
	v_add_f32_e32 v0, v0, v3
	v_add_f32_e32 v17, v17, v0
	v_mul_f32_e32 v0, v65, v65
	v_mul_f32_e32 v3, v67, v67
	v_fmac_f32_e32 v0, v64, v64
	v_fmac_f32_e32 v3, v66, v66
	v_add_f32_e32 v0, v0, v3
	v_add_f32_e32 v17, v17, v0
	v_cvt_pk_bf16_f32 v52, v52, v53
	v_cvt_pk_bf16_f32 v53, v54, v55
	v_cvt_pk_bf16_f32 v56, v56, v57
	v_cvt_pk_bf16_f32 v57, v58, v59
	v_cvt_pk_bf16_f32 v60, v60, v61
	v_cvt_pk_bf16_f32 v61, v62, v63
	v_cvt_pk_bf16_f32 v64, v64, v65
	v_cvt_pk_bf16_f32 v65, v66, v67
	global_store_dwordx2 v[32:33], v[52:53], off
	global_store_dwordx2 v[32:33], v[56:57], off offset:512
	global_store_dwordx2 v[32:33], v[60:61], off offset:1024
	global_store_dwordx2 v[32:33], v[64:65], off offset:1536
	v_lshl_add_u64 v[32:33], v[32:33], 0, s[44:45]
	s_waitcnt vmcnt(12)
	v_mul_f32_e32 v0, v69, v69
	v_mul_f32_e32 v3, v71, v71
	v_fmac_f32_e32 v0, v68, v68
	v_fmac_f32_e32 v3, v70, v70
	v_add_f32_e32 v18, v0, v3
	v_mul_f32_e32 v0, v73, v73
	v_mul_f32_e32 v3, v75, v75
	v_fmac_f32_e32 v0, v72, v72
	v_fmac_f32_e32 v3, v74, v74
	v_add_f32_e32 v0, v0, v3
	v_add_f32_e32 v18, v18, v0
	v_mul_f32_e32 v0, v77, v77
	v_mul_f32_e32 v3, v79, v79
	v_fmac_f32_e32 v0, v76, v76
	v_fmac_f32_e32 v3, v78, v78
	v_add_f32_e32 v0, v0, v3
	v_add_f32_e32 v18, v18, v0
	v_mul_f32_e32 v0, v81, v81
	v_mul_f32_e32 v3, v83, v83
	v_fmac_f32_e32 v0, v80, v80
	v_fmac_f32_e32 v3, v82, v82
	v_add_f32_e32 v0, v0, v3
	v_add_f32_e32 v18, v18, v0
	v_cvt_pk_bf16_f32 v68, v68, v69
	v_cvt_pk_bf16_f32 v69, v70, v71
	v_cvt_pk_bf16_f32 v72, v72, v73
	v_cvt_pk_bf16_f32 v73, v74, v75
	v_cvt_pk_bf16_f32 v76, v76, v77
	v_cvt_pk_bf16_f32 v77, v78, v79
	v_cvt_pk_bf16_f32 v80, v80, v81
	v_cvt_pk_bf16_f32 v81, v82, v83
	global_store_dwordx2 v[32:33], v[68:69], off
	global_store_dwordx2 v[32:33], v[72:73], off offset:512
	global_store_dwordx2 v[32:33], v[76:77], off offset:1024
	global_store_dwordx2 v[32:33], v[80:81], off offset:1536
	v_lshl_add_u64 v[32:33], v[32:33], 0, s[44:45]
	s_waitcnt vmcnt(12)
	v_mul_f32_e32 v0, v85, v85
	v_mul_f32_e32 v3, v87, v87
	v_fmac_f32_e32 v0, v84, v84
	v_fmac_f32_e32 v3, v86, v86
	v_add_f32_e32 v19, v0, v3
	v_mul_f32_e32 v0, v89, v89
	v_mul_f32_e32 v3, v91, v91
	v_fmac_f32_e32 v0, v88, v88
	v_fmac_f32_e32 v3, v90, v90
	v_add_f32_e32 v0, v0, v3
	v_add_f32_e32 v19, v19, v0
	v_mul_f32_e32 v0, v93, v93
	v_mul_f32_e32 v3, v95, v95
	v_fmac_f32_e32 v0, v92, v92
	v_fmac_f32_e32 v3, v94, v94
	v_add_f32_e32 v0, v0, v3
	v_add_f32_e32 v19, v19, v0
	v_mul_f32_e32 v0, v97, v97
	v_mul_f32_e32 v3, v99, v99
	v_fmac_f32_e32 v0, v96, v96
	v_fmac_f32_e32 v3, v98, v98
	v_add_f32_e32 v0, v0, v3
	v_add_f32_e32 v19, v19, v0
	v_cvt_pk_bf16_f32 v84, v84, v85
	v_cvt_pk_bf16_f32 v85, v86, v87
	v_cvt_pk_bf16_f32 v88, v88, v89
	v_cvt_pk_bf16_f32 v89, v90, v91
	v_cvt_pk_bf16_f32 v92, v92, v93
	v_cvt_pk_bf16_f32 v93, v94, v95
	v_cvt_pk_bf16_f32 v96, v96, v97
	v_cvt_pk_bf16_f32 v97, v98, v99
	global_store_dwordx2 v[32:33], v[84:85], off
	global_store_dwordx2 v[32:33], v[88:89], off offset:512
	global_store_dwordx2 v[32:33], v[92:93], off offset:1024
	global_store_dwordx2 v[32:33], v[96:97], off offset:1536
	ds_bpermute_b32 v24, v10, v16
	ds_bpermute_b32 v25, v10, v17
	ds_bpermute_b32 v26, v10, v18
	ds_bpermute_b32 v27, v10, v19
	s_waitcnt lgkmcnt(0)
	v_add_f32_e32 v16, v16, v24
	v_add_f32_e32 v17, v17, v25
	v_add_f32_e32 v18, v18, v26
	v_add_f32_e32 v19, v19, v27
	ds_bpermute_b32 v24, v11, v16
	ds_bpermute_b32 v25, v11, v17
	ds_bpermute_b32 v26, v11, v18
	ds_bpermute_b32 v27, v11, v19
	s_waitcnt lgkmcnt(0)
	v_add_f32_e32 v16, v16, v24
	v_add_f32_e32 v17, v17, v25
	v_add_f32_e32 v18, v18, v26
	v_add_f32_e32 v19, v19, v27
	ds_bpermute_b32 v24, v12, v16
	ds_bpermute_b32 v25, v12, v17
	ds_bpermute_b32 v26, v12, v18
	ds_bpermute_b32 v27, v12, v19
	s_waitcnt lgkmcnt(0)
	v_add_f32_e32 v16, v16, v24
	v_add_f32_e32 v17, v17, v25
	v_add_f32_e32 v18, v18, v26
	v_add_f32_e32 v19, v19, v27
	ds_bpermute_b32 v24, v13, v16
	ds_bpermute_b32 v25, v13, v17
	ds_bpermute_b32 v26, v13, v18
	ds_bpermute_b32 v27, v13, v19
	s_waitcnt lgkmcnt(0)
	v_add_f32_e32 v16, v16, v24
	v_add_f32_e32 v17, v17, v25
	v_add_f32_e32 v18, v18, v26
	v_add_f32_e32 v19, v19, v27
	ds_bpermute_b32 v24, v14, v16
	ds_bpermute_b32 v25, v14, v17
	ds_bpermute_b32 v26, v14, v18
	ds_bpermute_b32 v27, v14, v19
	s_waitcnt lgkmcnt(0)
	v_add_f32_e32 v16, v16, v24
	v_add_f32_e32 v17, v17, v25
	v_add_f32_e32 v18, v18, v26
	v_add_f32_e32 v19, v19, v27
	ds_bpermute_b32 v24, v15, v16
	ds_bpermute_b32 v25, v15, v17
	ds_bpermute_b32 v26, v15, v18
	ds_bpermute_b32 v27, v15, v19
	s_waitcnt lgkmcnt(0)
	v_add_f32_e32 v16, v16, v24
	v_add_f32_e32 v17, v17, v25
	v_add_f32_e32 v18, v18, v26
	v_add_f32_e32 v19, v19, v27
	v_cndmask_b32_e64 v16, 0, v16, s[42:43]
	v_cndmask_b32_e64 v17, 0, v17, s[42:43]
	v_cndmask_b32_e64 v18, 0, v18, s[42:43]
	v_cndmask_b32_e64 v19, 0, v19, s[42:43]
	s_and_saveexec_b64 s[24:25], vcc
	global_store_dword v[210:211], v16, off
	v_lshl_add_u64 v[210:211], v[210:211], 0, s[10:11]
	global_store_dword v[210:211], v17, off
	v_lshl_add_u64 v[210:211], v[210:211], 0, s[10:11]
	global_store_dword v[210:211], v18, off
	v_lshl_add_u64 v[210:211], v[210:211], 0, s[10:11]
	global_store_dword v[210:211], v19, off
	s_or_b64 exec, exec, s[24:25]
